# v31 + hand-written W_in epilogue (one dispatch per tile into three straight-line variants instead of per-pair scalar branches)
# baseline (speedup 1.0000x reference)
;     __device__ __forceinline__ void operator()(AccRef acc, const Unit& u, int wr, int wc, int fr, int fq) const {
;         const int row0 = u.pm * BM + wr * 64 + fr, col0 = u.pn * BM + wc * 32 + 8 * fq;
;         const bool sg = u.pn >= 16;
;         const bool ssm = (u.pn == 14) | (u.pn == 15);
;         const int cs = col0 - ZC_S;
;         bf16_t* const dst = ssm ? XS + (size_t)(cs >> 4) * T * 16 + (cs & 15) : Z + col0; const size_t pitch = ssm ? 16 : ZW; const size_t bjstep = ssm ? (size_t)8 * T * 16 : (size_t)HALF;
; #pragma unroll
;         for (int ai = 0; ai < 2; ++ai)
; #pragma unroll
;             for (int m = 0; m < 4; ++m) {
;                 const int row = row0 + ai * HALF + m * 16;
;                 const float rinv = rsqrtf((float)rss[row] * (1.f / (16777216.f * DM)) + EPS);
;                 const float nrl = rinv * -1.4426950408889634f;
.LBB0_390:
	v_lshl_add_u32 v162, s57, 8, v181
	v_ashrrev_i32_e32 v163, 31, v162
	v_lshl_add_u64 v[164:165], v[162:163], 3, s[42:43]
	global_load_dwordx2 v[194:195], v[164:165], off
	global_load_dwordx2 v[196:197], v[164:165], off offset:128
	global_load_dwordx2 v[198:199], v[164:165], off offset:256
	global_load_dwordx2 v[200:201], v[164:165], off offset:384
	global_load_dwordx2 v[202:203], v[164:165], off offset:1024
	global_load_dwordx2 v[204:205], v[164:165], off offset:1152
	global_load_dwordx2 v[206:207], v[164:165], off offset:1280
	global_load_dwordx2 v[208:209], v[164:165], off offset:1408
	v_mad_i64_i32 v[234:235], s[40:41], s22, v162, 0
	s_mov_b32 s101, 0
	v_lshl_add_u64 v[234:235], v[234:235], 1, v[160:161]
	s_waitcnt vmcnt(0)
	v_ffbh_u32_e32 v210, v195
	v_ffbh_u32_e32 v211, v197
	v_ffbh_u32_e32 v212, v199
	v_ffbh_u32_e32 v213, v201
	v_ffbh_u32_e32 v214, v203
	v_ffbh_u32_e32 v215, v205
	v_ffbh_u32_e32 v216, v207
	v_ffbh_u32_e32 v217, v209
	v_min_u32_e32 v210, 32, v210
	v_min_u32_e32 v211, 32, v211
	v_min_u32_e32 v212, 32, v212
	v_min_u32_e32 v213, 32, v213
	v_min_u32_e32 v214, 32, v214
	v_min_u32_e32 v215, 32, v215
	v_min_u32_e32 v216, 32, v216
	v_min_u32_e32 v217, 32, v217
	v_lshlrev_b64 v[194:195], v210, v[194:195]
	v_lshlrev_b64 v[196:197], v211, v[196:197]
	v_lshlrev_b64 v[198:199], v212, v[198:199]
	v_lshlrev_b64 v[200:201], v213, v[200:201]
	v_lshlrev_b64 v[202:203], v214, v[202:203]
	v_lshlrev_b64 v[204:205], v215, v[204:205]
	v_lshlrev_b64 v[206:207], v216, v[206:207]
	v_lshlrev_b64 v[208:209], v217, v[208:209]
	v_min_u32_e32 v194, 1, v194
	v_min_u32_e32 v196, 1, v196
	v_min_u32_e32 v198, 1, v198
	v_min_u32_e32 v200, 1, v200
	v_min_u32_e32 v202, 1, v202
	v_min_u32_e32 v204, 1, v204
	v_min_u32_e32 v206, 1, v206
	v_min_u32_e32 v208, 1, v208
	v_or_b32_e32 v194, v195, v194
	v_or_b32_e32 v196, v197, v196
	v_or_b32_e32 v198, v199, v198
	v_or_b32_e32 v200, v201, v200
	v_or_b32_e32 v202, v203, v202
	v_or_b32_e32 v204, v205, v204
	v_or_b32_e32 v206, v207, v206
	v_or_b32_e32 v208, v209, v208
	v_cvt_f32_u32_e32 v194, v194
	v_cvt_f32_u32_e32 v196, v196
	v_cvt_f32_u32_e32 v198, v198
	v_cvt_f32_u32_e32 v200, v200
	v_cvt_f32_u32_e32 v202, v202
	v_cvt_f32_u32_e32 v204, v204
	v_cvt_f32_u32_e32 v206, v206
	v_cvt_f32_u32_e32 v208, v208
	v_sub_u32_e32 v210, 32, v210
	v_sub_u32_e32 v211, 32, v211
	v_sub_u32_e32 v212, 32, v212
	v_sub_u32_e32 v213, 32, v213
	v_sub_u32_e32 v214, 32, v214
	v_sub_u32_e32 v215, 32, v215
	v_sub_u32_e32 v216, 32, v216
	v_sub_u32_e32 v217, 32, v217
	v_ldexp_f32 v210, v194, v210
	v_ldexp_f32 v211, v196, v211
	v_ldexp_f32 v212, v198, v212
	v_ldexp_f32 v213, v200, v213
	v_ldexp_f32 v214, v202, v214
	v_ldexp_f32 v215, v204, v215
	v_ldexp_f32 v216, v206, v216
	v_ldexp_f32 v217, v208, v217
	v_fmamk_f32 v210, v210, 0x2e000000, v176
	v_fmamk_f32 v211, v211, 0x2e000000, v176
	v_fmamk_f32 v212, v212, 0x2e000000, v176
	v_fmamk_f32 v213, v213, 0x2e000000, v176
	v_fmamk_f32 v214, v214, 0x2e000000, v176
	v_fmamk_f32 v215, v215, 0x2e000000, v176
	v_fmamk_f32 v216, v216, 0x2e000000, v176
	v_fmamk_f32 v217, v217, 0x2e000000, v176
	v_mul_f32_e32 v194, 0x4b800000, v210
	v_mul_f32_e32 v196, 0x4b800000, v211
	v_mul_f32_e32 v198, 0x4b800000, v212
	v_mul_f32_e32 v200, 0x4b800000, v213
	v_mul_f32_e32 v202, 0x4b800000, v214
	v_mul_f32_e32 v204, 0x4b800000, v215
	v_mul_f32_e32 v206, 0x4b800000, v216
	v_mul_f32_e32 v208, 0x4b800000, v217
	v_cmp_gt_f32_e32 vcc, s7, v210
	s_nop 1
	v_cndmask_b32_e32 v210, v210, v194, vcc
	v_rsq_f32_e32 v210, v210
	s_nop 0
	v_mul_f32_e32 v194, 0x45800000, v210
	v_cndmask_b32_e32 v218, v210, v194, vcc
	v_cmp_gt_f32_e32 vcc, s7, v211
	s_nop 1
	v_cndmask_b32_e32 v211, v211, v196, vcc
	v_rsq_f32_e32 v211, v211
	s_nop 0
	v_mul_f32_e32 v196, 0x45800000, v211
	v_cndmask_b32_e32 v220, v211, v196, vcc
	v_cmp_gt_f32_e32 vcc, s7, v212
	s_nop 1
	v_cndmask_b32_e32 v212, v212, v198, vcc
	v_rsq_f32_e32 v212, v212
	s_nop 0
	v_mul_f32_e32 v198, 0x45800000, v212
	v_cndmask_b32_e32 v222, v212, v198, vcc
	v_cmp_gt_f32_e32 vcc, s7, v213
	s_nop 1
	v_cndmask_b32_e32 v213, v213, v200, vcc
	v_rsq_f32_e32 v213, v213
	s_nop 0
	v_mul_f32_e32 v200, 0x45800000, v213
	v_cndmask_b32_e32 v224, v213, v200, vcc
	v_cmp_gt_f32_e32 vcc, s7, v214
	s_nop 1
	v_cndmask_b32_e32 v214, v214, v202, vcc
	v_rsq_f32_e32 v214, v214
	s_nop 0
	v_mul_f32_e32 v202, 0x45800000, v214
	v_cndmask_b32_e32 v226, v214, v202, vcc
	v_cmp_gt_f32_e32 vcc, s7, v215
	s_nop 1
	v_cndmask_b32_e32 v215, v215, v204, vcc
	v_rsq_f32_e32 v215, v215
	s_nop 0
	v_mul_f32_e32 v204, 0x45800000, v215
	v_cndmask_b32_e32 v228, v215, v204, vcc
	v_cmp_gt_f32_e32 vcc, s7, v216
	s_nop 1
	v_cndmask_b32_e32 v216, v216, v206, vcc
	v_rsq_f32_e32 v216, v216
	s_nop 0
	v_mul_f32_e32 v206, 0x45800000, v216
	v_cndmask_b32_e32 v230, v216, v206, vcc
	v_cmp_gt_f32_e32 vcc, s7, v217
	s_nop 1
	v_cndmask_b32_e32 v217, v217, v208, vcc
	v_rsq_f32_e32 v217, v217
	s_nop 0
	v_mul_f32_e32 v208, 0x45800000, v217
	v_cndmask_b32_e32 v232, v217, v208, vcc
	s_cmp_eq_u32 s22, 16
	s_cbranch_scc1 .Lwin_ssm
	s_cmp_lt_i32 s56, 16
	s_cbranch_scc0 .Lwin_sg
; __device__ __forceinline__ unsigned pk2(float lo, float hi) { const f32v2_t v = {lo, hi}; const bf16v2_t b = __builtin_convertvector(v, bf16v2_t); return __builtin_bit_cast(unsigned, b); }
; #define ST_OUT(p, v) __builtin_nontemporal_store((v), (p))
;     __device__ __forceinline__ void operator()(AccRef acc, const Unit& u, int wr, int wc, int fr, int fq) const {
;     ...
; #pragma unroll
;                 for (int bj = 0; bj < 2; ++bj) {
;                     unsigned ow[4];
; #pragma unroll
;                     for (int n = 0; n < 2; ++n)
; #pragma unroll
;                         for (int jp = 0; jp < 2; ++jp) {
;                             const f32v2_t av = {acc[ai][bj][m][n][2 * jp], acc[ai][bj][m][n][2 * jp + 1]};
;                             f32v2_t hv;
;                             if (sg) { const f32v2_t t = av * nrl; f32v2_t e; e.x = __builtin_amdgcn_exp2f(t.x); e.y = __builtin_amdgcn_exp2f(t.y); const f32v2_t d = e + 1.0f;
;                                 hv.x = __builtin_amdgcn_rcpf(d.x); hv.y = __builtin_amdgcn_rcpf(d.y); }
;                             else hv = av * rinv;
;                             ow[n * 2 + jp] = pk2(hv.x, hv.y);
;                         }
;                     u32x4 o; o.x = ow[0]; o.y = ow[1]; o.z = ow[2]; o.w = ow[3];
;                     ST_OUT((u32x4*)(dst + (size_t)row * pitch + bj * bjstep), o);
;                 }
	v_pk_mul_f32 v[124:125], v[124:125], v[218:219] op_sel_hi:[1,0]
	v_pk_mul_f32 v[126:127], v[126:127], v[218:219] op_sel_hi:[1,0]
	v_pk_mul_f32 v[120:121], v[120:121], v[218:219] op_sel_hi:[1,0]
	v_pk_mul_f32 v[122:123], v[122:123], v[218:219] op_sel_hi:[1,0]
	s_mov_b32 s100, 0x0
	v_lshl_add_u64 v[236:237], v[234:235], 0, s[100:101]
	v_cvt_pk_bf16_f32 v124, v124, v125
	v_cvt_pk_bf16_f32 v125, v126, v127
	v_cvt_pk_bf16_f32 v126, v120, v121
	v_cvt_pk_bf16_f32 v127, v122, v123
	global_store_dwordx4 v[236:237], v[124:127], off nt
	v_pk_mul_f32 v[116:117], v[116:117], v[218:219] op_sel_hi:[1,0]
	v_pk_mul_f32 v[118:119], v[118:119], v[218:219] op_sel_hi:[1,0]
	v_pk_mul_f32 v[112:113], v[112:113], v[218:219] op_sel_hi:[1,0]
	v_pk_mul_f32 v[114:115], v[114:115], v[218:219] op_sel_hi:[1,0]
	s_mov_b32 s100, 0x0
	v_lshl_add_u64 v[236:237], v[234:235], 0, s[100:101]
	v_cvt_pk_bf16_f32 v116, v116, v117
	v_cvt_pk_bf16_f32 v117, v118, v119
	v_cvt_pk_bf16_f32 v118, v112, v113
	v_cvt_pk_bf16_f32 v119, v114, v115
	global_store_dwordx4 v[236:237], v[116:119], off offset:256 nt
	v_pk_mul_f32 v[108:109], v[108:109], v[220:221] op_sel_hi:[1,0]
	v_pk_mul_f32 v[110:111], v[110:111], v[220:221] op_sel_hi:[1,0]
	v_pk_mul_f32 v[104:105], v[104:105], v[220:221] op_sel_hi:[1,0]
	v_pk_mul_f32 v[106:107], v[106:107], v[220:221] op_sel_hi:[1,0]
	s_mov_b32 s100, 0x50000
	v_lshl_add_u64 v[236:237], v[234:235], 0, s[100:101]
	v_cvt_pk_bf16_f32 v108, v108, v109
	v_cvt_pk_bf16_f32 v109, v110, v111
	v_cvt_pk_bf16_f32 v110, v104, v105
	v_cvt_pk_bf16_f32 v111, v106, v107
	global_store_dwordx4 v[236:237], v[108:111], off nt
	v_pk_mul_f32 v[100:101], v[100:101], v[220:221] op_sel_hi:[1,0]
	v_pk_mul_f32 v[102:103], v[102:103], v[220:221] op_sel_hi:[1,0]
	v_pk_mul_f32 v[96:97], v[96:97], v[220:221] op_sel_hi:[1,0]
	v_pk_mul_f32 v[98:99], v[98:99], v[220:221] op_sel_hi:[1,0]
	s_mov_b32 s100, 0x50000
	v_lshl_add_u64 v[236:237], v[234:235], 0, s[100:101]
	v_cvt_pk_bf16_f32 v100, v100, v101
	v_cvt_pk_bf16_f32 v101, v102, v103
	v_cvt_pk_bf16_f32 v102, v96, v97
	v_cvt_pk_bf16_f32 v103, v98, v99
	global_store_dwordx4 v[236:237], v[100:103], off offset:256 nt
	v_pk_mul_f32 v[92:93], v[92:93], v[222:223] op_sel_hi:[1,0]
	v_pk_mul_f32 v[94:95], v[94:95], v[222:223] op_sel_hi:[1,0]
	v_pk_mul_f32 v[88:89], v[88:89], v[222:223] op_sel_hi:[1,0]
	v_pk_mul_f32 v[90:91], v[90:91], v[222:223] op_sel_hi:[1,0]
	s_mov_b32 s100, 0xa0000
	v_lshl_add_u64 v[236:237], v[234:235], 0, s[100:101]
	v_cvt_pk_bf16_f32 v92, v92, v93
	v_cvt_pk_bf16_f32 v93, v94, v95
	v_cvt_pk_bf16_f32 v94, v88, v89
	v_cvt_pk_bf16_f32 v95, v90, v91
	global_store_dwordx4 v[236:237], v[92:95], off nt
	v_pk_mul_f32 v[84:85], v[84:85], v[222:223] op_sel_hi:[1,0]
	v_pk_mul_f32 v[86:87], v[86:87], v[222:223] op_sel_hi:[1,0]
	v_pk_mul_f32 v[80:81], v[80:81], v[222:223] op_sel_hi:[1,0]
	v_pk_mul_f32 v[82:83], v[82:83], v[222:223] op_sel_hi:[1,0]
	s_mov_b32 s100, 0xa0000
	v_lshl_add_u64 v[236:237], v[234:235], 0, s[100:101]
	v_cvt_pk_bf16_f32 v84, v84, v85
	v_cvt_pk_bf16_f32 v85, v86, v87
	v_cvt_pk_bf16_f32 v86, v80, v81
	v_cvt_pk_bf16_f32 v87, v82, v83
	global_store_dwordx4 v[236:237], v[84:87], off offset:256 nt
	v_pk_mul_f32 v[76:77], v[76:77], v[224:225] op_sel_hi:[1,0]
	v_pk_mul_f32 v[78:79], v[78:79], v[224:225] op_sel_hi:[1,0]
	v_pk_mul_f32 v[72:73], v[72:73], v[224:225] op_sel_hi:[1,0]
	v_pk_mul_f32 v[74:75], v[74:75], v[224:225] op_sel_hi:[1,0]
	s_mov_b32 s100, 0xf0000
	v_lshl_add_u64 v[236:237], v[234:235], 0, s[100:101]
	v_cvt_pk_bf16_f32 v76, v76, v77
	v_cvt_pk_bf16_f32 v77, v78, v79
	v_cvt_pk_bf16_f32 v78, v72, v73
	v_cvt_pk_bf16_f32 v79, v74, v75
	global_store_dwordx4 v[236:237], v[76:79], off nt
	v_pk_mul_f32 v[68:69], v[68:69], v[224:225] op_sel_hi:[1,0]
	v_pk_mul_f32 v[70:71], v[70:71], v[224:225] op_sel_hi:[1,0]
	v_pk_mul_f32 v[64:65], v[64:65], v[224:225] op_sel_hi:[1,0]
	v_pk_mul_f32 v[66:67], v[66:67], v[224:225] op_sel_hi:[1,0]
	s_mov_b32 s100, 0xf0000
	v_lshl_add_u64 v[236:237], v[234:235], 0, s[100:101]
	v_cvt_pk_bf16_f32 v68, v68, v69
	v_cvt_pk_bf16_f32 v69, v70, v71
	v_cvt_pk_bf16_f32 v70, v64, v65
	v_cvt_pk_bf16_f32 v71, v66, v67
	global_store_dwordx4 v[236:237], v[68:71], off offset:256 nt
	v_pk_mul_f32 v[60:61], v[60:61], v[226:227] op_sel_hi:[1,0]
	v_pk_mul_f32 v[62:63], v[62:63], v[226:227] op_sel_hi:[1,0]
	v_pk_mul_f32 v[56:57], v[56:57], v[226:227] op_sel_hi:[1,0]
	v_pk_mul_f32 v[58:59], v[58:59], v[226:227] op_sel_hi:[1,0]
	s_mov_b32 s100, 0x280000
	v_lshl_add_u64 v[236:237], v[234:235], 0, s[100:101]
	v_cvt_pk_bf16_f32 v60, v60, v61
	v_cvt_pk_bf16_f32 v61, v62, v63
	v_cvt_pk_bf16_f32 v62, v56, v57
	v_cvt_pk_bf16_f32 v63, v58, v59
	global_store_dwordx4 v[236:237], v[60:63], off nt
	v_pk_mul_f32 v[52:53], v[52:53], v[226:227] op_sel_hi:[1,0]
	v_pk_mul_f32 v[54:55], v[54:55], v[226:227] op_sel_hi:[1,0]
	v_pk_mul_f32 v[48:49], v[48:49], v[226:227] op_sel_hi:[1,0]
	v_pk_mul_f32 v[50:51], v[50:51], v[226:227] op_sel_hi:[1,0]
	s_mov_b32 s100, 0x280000
	v_lshl_add_u64 v[236:237], v[234:235], 0, s[100:101]
	v_cvt_pk_bf16_f32 v52, v52, v53
	v_cvt_pk_bf16_f32 v53, v54, v55
	v_cvt_pk_bf16_f32 v54, v48, v49
	v_cvt_pk_bf16_f32 v55, v50, v51
	global_store_dwordx4 v[236:237], v[52:55], off offset:256 nt
	v_pk_mul_f32 v[44:45], v[44:45], v[228:229] op_sel_hi:[1,0]
	v_pk_mul_f32 v[46:47], v[46:47], v[228:229] op_sel_hi:[1,0]
	v_pk_mul_f32 v[40:41], v[40:41], v[228:229] op_sel_hi:[1,0]
	v_pk_mul_f32 v[42:43], v[42:43], v[228:229] op_sel_hi:[1,0]
	s_mov_b32 s100, 0x2d0000
	v_lshl_add_u64 v[236:237], v[234:235], 0, s[100:101]
	v_cvt_pk_bf16_f32 v44, v44, v45
	v_cvt_pk_bf16_f32 v45, v46, v47
	v_cvt_pk_bf16_f32 v46, v40, v41
; __device__ __forceinline__ unsigned pk2(float lo, float hi) { const f32v2_t v = {lo, hi}; const bf16v2_t b = __builtin_convertvector(v, bf16v2_t); return __builtin_bit_cast(unsigned, b); }
; #define ST_OUT(p, v) __builtin_nontemporal_store((v), (p))
;     __device__ __forceinline__ void operator()(AccRef acc, const Unit& u, int wr, int wc, int fr, int fq) const {
;     ...
;         bf16_t* const dst = ssm ? XS + (size_t)(cs >> 4) * T * 16 + (cs & 15) : Z + col0; const size_t pitch = ssm ? 16 : ZW; const size_t bjstep = ssm ? (size_t)8 * T * 16 : (size_t)HALF;
; #pragma unroll
;         for (int ai = 0; ai < 2; ++ai)
; #pragma unroll
;             for (int m = 0; m < 4; ++m) {
;                 const int row = row0 + ai * HALF + m * 16;
;                 const float rinv = rsqrtf((float)rss[row] * (1.f / (16777216.f * DM)) + EPS);
;                 const float nrl = rinv * -1.4426950408889634f;
; #pragma unroll
;                 for (int bj = 0; bj < 2; ++bj) {
;                     unsigned ow[4];
; #pragma unroll
;                     for (int n = 0; n < 2; ++n)
; #pragma unroll
;                         for (int jp = 0; jp < 2; ++jp) {
;                             const f32v2_t av = {acc[ai][bj][m][n][2 * jp], acc[ai][bj][m][n][2 * jp + 1]};
;                             f32v2_t hv;
;                             if (sg) { const f32v2_t t = av * nrl; f32v2_t e; e.x = __builtin_amdgcn_exp2f(t.x); e.y = __builtin_amdgcn_exp2f(t.y); const f32v2_t d = e + 1.0f;
;                                 hv.x = __builtin_amdgcn_rcpf(d.x); hv.y = __builtin_amdgcn_rcpf(d.y); }
;                             else hv = av * rinv;
;                             ow[n * 2 + jp] = pk2(hv.x, hv.y);
;                         }
;                     u32x4 o; o.x = ow[0]; o.y = ow[1]; o.z = ow[2]; o.w = ow[3];
;                     ST_OUT((u32x4*)(dst + (size_t)row * pitch + bj * bjstep), o);
;                 }
	v_cvt_pk_bf16_f32 v47, v42, v43
	global_store_dwordx4 v[236:237], v[44:47], off nt
	v_pk_mul_f32 v[36:37], v[36:37], v[228:229] op_sel_hi:[1,0]
	v_pk_mul_f32 v[38:39], v[38:39], v[228:229] op_sel_hi:[1,0]
	v_pk_mul_f32 v[32:33], v[32:33], v[228:229] op_sel_hi:[1,0]
	v_pk_mul_f32 v[34:35], v[34:35], v[228:229] op_sel_hi:[1,0]
	s_mov_b32 s100, 0x2d0000
	v_lshl_add_u64 v[236:237], v[234:235], 0, s[100:101]
	v_cvt_pk_bf16_f32 v36, v36, v37
	v_cvt_pk_bf16_f32 v37, v38, v39
	v_cvt_pk_bf16_f32 v38, v32, v33
	v_cvt_pk_bf16_f32 v39, v34, v35
	global_store_dwordx4 v[236:237], v[36:39], off offset:256 nt
	v_pk_mul_f32 v[28:29], v[28:29], v[230:231] op_sel_hi:[1,0]
	v_pk_mul_f32 v[30:31], v[30:31], v[230:231] op_sel_hi:[1,0]
	v_pk_mul_f32 v[24:25], v[24:25], v[230:231] op_sel_hi:[1,0]
	v_pk_mul_f32 v[26:27], v[26:27], v[230:231] op_sel_hi:[1,0]
	s_mov_b32 s100, 0x320000
	v_lshl_add_u64 v[236:237], v[234:235], 0, s[100:101]
	v_cvt_pk_bf16_f32 v28, v28, v29
	v_cvt_pk_bf16_f32 v29, v30, v31
	v_cvt_pk_bf16_f32 v30, v24, v25
	v_cvt_pk_bf16_f32 v31, v26, v27
	global_store_dwordx4 v[236:237], v[28:31], off nt
	v_pk_mul_f32 v[20:21], v[20:21], v[230:231] op_sel_hi:[1,0]
	v_pk_mul_f32 v[22:23], v[22:23], v[230:231] op_sel_hi:[1,0]
	v_pk_mul_f32 v[16:17], v[16:17], v[230:231] op_sel_hi:[1,0]
	v_pk_mul_f32 v[18:19], v[18:19], v[230:231] op_sel_hi:[1,0]
	s_mov_b32 s100, 0x320000
	v_lshl_add_u64 v[236:237], v[234:235], 0, s[100:101]
	v_cvt_pk_bf16_f32 v20, v20, v21
	v_cvt_pk_bf16_f32 v21, v22, v23
	v_cvt_pk_bf16_f32 v22, v16, v17
	v_cvt_pk_bf16_f32 v23, v18, v19
	global_store_dwordx4 v[236:237], v[20:23], off offset:256 nt
	v_pk_mul_f32 v[12:13], v[12:13], v[232:233] op_sel_hi:[1,0]
	v_pk_mul_f32 v[14:15], v[14:15], v[232:233] op_sel_hi:[1,0]
	v_pk_mul_f32 v[8:9], v[8:9], v[232:233] op_sel_hi:[1,0]
	v_pk_mul_f32 v[10:11], v[10:11], v[232:233] op_sel_hi:[1,0]
	s_mov_b32 s100, 0x370000
	v_lshl_add_u64 v[236:237], v[234:235], 0, s[100:101]
	v_cvt_pk_bf16_f32 v12, v12, v13
	v_cvt_pk_bf16_f32 v13, v14, v15
	v_cvt_pk_bf16_f32 v14, v8, v9
	v_cvt_pk_bf16_f32 v15, v10, v11
	global_store_dwordx4 v[236:237], v[12:15], off nt
	v_pk_mul_f32 v[4:5], v[4:5], v[232:233] op_sel_hi:[1,0]
	v_pk_mul_f32 v[6:7], v[6:7], v[232:233] op_sel_hi:[1,0]
	v_pk_mul_f32 v[0:1], v[0:1], v[232:233] op_sel_hi:[1,0]
	v_pk_mul_f32 v[2:3], v[2:3], v[232:233] op_sel_hi:[1,0]
	s_mov_b32 s100, 0x370000
	v_lshl_add_u64 v[236:237], v[234:235], 0, s[100:101]
	v_cvt_pk_bf16_f32 v4, v4, v5
	v_cvt_pk_bf16_f32 v5, v6, v7
	v_cvt_pk_bf16_f32 v6, v0, v1
	v_cvt_pk_bf16_f32 v7, v2, v3
	global_store_dwordx4 v[236:237], v[4:7], off offset:256 nt
	s_branch .Lwin_done
.Lwin_ssm:
	v_pk_mul_f32 v[124:125], v[124:125], v[218:219] op_sel_hi:[1,0]
	v_pk_mul_f32 v[126:127], v[126:127], v[218:219] op_sel_hi:[1,0]
	v_pk_mul_f32 v[120:121], v[120:121], v[218:219] op_sel_hi:[1,0]
	v_pk_mul_f32 v[122:123], v[122:123], v[218:219] op_sel_hi:[1,0]
	s_mov_b32 s100, 0x0
	v_lshl_add_u64 v[236:237], v[234:235], 0, s[100:101]
	v_cvt_pk_bf16_f32 v124, v124, v125
	v_cvt_pk_bf16_f32 v125, v126, v127
	v_cvt_pk_bf16_f32 v126, v120, v121
	v_cvt_pk_bf16_f32 v127, v122, v123
	global_store_dwordx4 v[236:237], v[124:127], off nt
	v_pk_mul_f32 v[116:117], v[116:117], v[218:219] op_sel_hi:[1,0]
	v_pk_mul_f32 v[118:119], v[118:119], v[218:219] op_sel_hi:[1,0]
	v_pk_mul_f32 v[112:113], v[112:113], v[218:219] op_sel_hi:[1,0]
	v_pk_mul_f32 v[114:115], v[114:115], v[218:219] op_sel_hi:[1,0]
	s_mov_b32 s100, 0x400000
	v_lshl_add_u64 v[236:237], v[234:235], 0, s[100:101]
	v_cvt_pk_bf16_f32 v116, v116, v117
	v_cvt_pk_bf16_f32 v117, v118, v119
	v_cvt_pk_bf16_f32 v118, v112, v113
	v_cvt_pk_bf16_f32 v119, v114, v115
	global_store_dwordx4 v[236:237], v[116:119], off nt
	v_pk_mul_f32 v[108:109], v[108:109], v[220:221] op_sel_hi:[1,0]
	v_pk_mul_f32 v[110:111], v[110:111], v[220:221] op_sel_hi:[1,0]
	v_pk_mul_f32 v[104:105], v[104:105], v[220:221] op_sel_hi:[1,0]
	v_pk_mul_f32 v[106:107], v[106:107], v[220:221] op_sel_hi:[1,0]
	s_mov_b32 s100, 0x200
	v_lshl_add_u64 v[236:237], v[234:235], 0, s[100:101]
	v_cvt_pk_bf16_f32 v108, v108, v109
	v_cvt_pk_bf16_f32 v109, v110, v111
	v_cvt_pk_bf16_f32 v110, v104, v105
	v_cvt_pk_bf16_f32 v111, v106, v107
	global_store_dwordx4 v[236:237], v[108:111], off nt
	v_pk_mul_f32 v[100:101], v[100:101], v[220:221] op_sel_hi:[1,0]
	v_pk_mul_f32 v[102:103], v[102:103], v[220:221] op_sel_hi:[1,0]
	v_pk_mul_f32 v[96:97], v[96:97], v[220:221] op_sel_hi:[1,0]
	v_pk_mul_f32 v[98:99], v[98:99], v[220:221] op_sel_hi:[1,0]
	s_mov_b32 s100, 0x400200
	v_lshl_add_u64 v[236:237], v[234:235], 0, s[100:101]
	v_cvt_pk_bf16_f32 v100, v100, v101
	v_cvt_pk_bf16_f32 v101, v102, v103
	v_cvt_pk_bf16_f32 v102, v96, v97
	v_cvt_pk_bf16_f32 v103, v98, v99
	global_store_dwordx4 v[236:237], v[100:103], off nt
	v_pk_mul_f32 v[92:93], v[92:93], v[222:223] op_sel_hi:[1,0]
	v_pk_mul_f32 v[94:95], v[94:95], v[222:223] op_sel_hi:[1,0]
	v_pk_mul_f32 v[88:89], v[88:89], v[222:223] op_sel_hi:[1,0]
	v_pk_mul_f32 v[90:91], v[90:91], v[222:223] op_sel_hi:[1,0]
	s_mov_b32 s100, 0x400
	v_lshl_add_u64 v[236:237], v[234:235], 0, s[100:101]
	v_cvt_pk_bf16_f32 v92, v92, v93
	v_cvt_pk_bf16_f32 v93, v94, v95
	v_cvt_pk_bf16_f32 v94, v88, v89
	v_cvt_pk_bf16_f32 v95, v90, v91
	global_store_dwordx4 v[236:237], v[92:95], off nt
	v_pk_mul_f32 v[84:85], v[84:85], v[222:223] op_sel_hi:[1,0]
	v_pk_mul_f32 v[86:87], v[86:87], v[222:223] op_sel_hi:[1,0]
	v_pk_mul_f32 v[80:81], v[80:81], v[222:223] op_sel_hi:[1,0]
	v_pk_mul_f32 v[82:83], v[82:83], v[222:223] op_sel_hi:[1,0]
	s_mov_b32 s100, 0x400400
	v_lshl_add_u64 v[236:237], v[234:235], 0, s[100:101]
	v_cvt_pk_bf16_f32 v84, v84, v85
; __device__ __forceinline__ unsigned pk2(float lo, float hi) { const f32v2_t v = {lo, hi}; const bf16v2_t b = __builtin_convertvector(v, bf16v2_t); return __builtin_bit_cast(unsigned, b); }
; #define ST_OUT(p, v) __builtin_nontemporal_store((v), (p))
;     __device__ __forceinline__ void operator()(AccRef acc, const Unit& u, int wr, int wc, int fr, int fq) const {
;     ...
; #pragma unroll
;         for (int ai = 0; ai < 2; ++ai)
; #pragma unroll
;             for (int m = 0; m < 4; ++m) {
;                 const int row = row0 + ai * HALF + m * 16;
;                 const float rinv = rsqrtf((float)rss[row] * (1.f / (16777216.f * DM)) + EPS);
;                 const float nrl = rinv * -1.4426950408889634f;
; #pragma unroll
;                 for (int bj = 0; bj < 2; ++bj) {
;                     unsigned ow[4];
; #pragma unroll
;                     for (int n = 0; n < 2; ++n)
; #pragma unroll
;                         for (int jp = 0; jp < 2; ++jp) {
;                             const f32v2_t av = {acc[ai][bj][m][n][2 * jp], acc[ai][bj][m][n][2 * jp + 1]};
;                             f32v2_t hv;
;                             if (sg) { const f32v2_t t = av * nrl; f32v2_t e; e.x = __builtin_amdgcn_exp2f(t.x); e.y = __builtin_amdgcn_exp2f(t.y); const f32v2_t d = e + 1.0f;
;                                 hv.x = __builtin_amdgcn_rcpf(d.x); hv.y = __builtin_amdgcn_rcpf(d.y); }
;                             else hv = av * rinv;
;                             ow[n * 2 + jp] = pk2(hv.x, hv.y);
;                         }
;                     u32x4 o; o.x = ow[0]; o.y = ow[1]; o.z = ow[2]; o.w = ow[3];
;                     ST_OUT((u32x4*)(dst + (size_t)row * pitch + bj * bjstep), o);
;                 }
	v_cvt_pk_bf16_f32 v85, v86, v87
	v_cvt_pk_bf16_f32 v86, v80, v81
	v_cvt_pk_bf16_f32 v87, v82, v83
	global_store_dwordx4 v[236:237], v[84:87], off nt
	v_pk_mul_f32 v[76:77], v[76:77], v[224:225] op_sel_hi:[1,0]
	v_pk_mul_f32 v[78:79], v[78:79], v[224:225] op_sel_hi:[1,0]
	v_pk_mul_f32 v[72:73], v[72:73], v[224:225] op_sel_hi:[1,0]
	v_pk_mul_f32 v[74:75], v[74:75], v[224:225] op_sel_hi:[1,0]
	s_mov_b32 s100, 0x600
	v_lshl_add_u64 v[236:237], v[234:235], 0, s[100:101]
	v_cvt_pk_bf16_f32 v76, v76, v77
	v_cvt_pk_bf16_f32 v77, v78, v79
	v_cvt_pk_bf16_f32 v78, v72, v73
	v_cvt_pk_bf16_f32 v79, v74, v75
	global_store_dwordx4 v[236:237], v[76:79], off nt
	v_pk_mul_f32 v[68:69], v[68:69], v[224:225] op_sel_hi:[1,0]
	v_pk_mul_f32 v[70:71], v[70:71], v[224:225] op_sel_hi:[1,0]
	v_pk_mul_f32 v[64:65], v[64:65], v[224:225] op_sel_hi:[1,0]
	v_pk_mul_f32 v[66:67], v[66:67], v[224:225] op_sel_hi:[1,0]
	s_mov_b32 s100, 0x400600
	v_lshl_add_u64 v[236:237], v[234:235], 0, s[100:101]
	v_cvt_pk_bf16_f32 v68, v68, v69
	v_cvt_pk_bf16_f32 v69, v70, v71
	v_cvt_pk_bf16_f32 v70, v64, v65
	v_cvt_pk_bf16_f32 v71, v66, v67
	global_store_dwordx4 v[236:237], v[68:71], off nt
	v_pk_mul_f32 v[60:61], v[60:61], v[226:227] op_sel_hi:[1,0]
	v_pk_mul_f32 v[62:63], v[62:63], v[226:227] op_sel_hi:[1,0]
	v_pk_mul_f32 v[56:57], v[56:57], v[226:227] op_sel_hi:[1,0]
	v_pk_mul_f32 v[58:59], v[58:59], v[226:227] op_sel_hi:[1,0]
	s_mov_b32 s100, 0x1000
	v_lshl_add_u64 v[236:237], v[234:235], 0, s[100:101]
	v_cvt_pk_bf16_f32 v60, v60, v61
	v_cvt_pk_bf16_f32 v61, v62, v63
	v_cvt_pk_bf16_f32 v62, v56, v57
	v_cvt_pk_bf16_f32 v63, v58, v59
	global_store_dwordx4 v[236:237], v[60:63], off nt
	v_pk_mul_f32 v[52:53], v[52:53], v[226:227] op_sel_hi:[1,0]
	v_pk_mul_f32 v[54:55], v[54:55], v[226:227] op_sel_hi:[1,0]
	v_pk_mul_f32 v[48:49], v[48:49], v[226:227] op_sel_hi:[1,0]
	v_pk_mul_f32 v[50:51], v[50:51], v[226:227] op_sel_hi:[1,0]
	s_mov_b32 s100, 0x401000
	v_lshl_add_u64 v[236:237], v[234:235], 0, s[100:101]
	v_cvt_pk_bf16_f32 v52, v52, v53
	v_cvt_pk_bf16_f32 v53, v54, v55
	v_cvt_pk_bf16_f32 v54, v48, v49
	v_cvt_pk_bf16_f32 v55, v50, v51
	global_store_dwordx4 v[236:237], v[52:55], off nt
	v_pk_mul_f32 v[44:45], v[44:45], v[228:229] op_sel_hi:[1,0]
	v_pk_mul_f32 v[46:47], v[46:47], v[228:229] op_sel_hi:[1,0]
	v_pk_mul_f32 v[40:41], v[40:41], v[228:229] op_sel_hi:[1,0]
	v_pk_mul_f32 v[42:43], v[42:43], v[228:229] op_sel_hi:[1,0]
	s_mov_b32 s100, 0x1200
	v_lshl_add_u64 v[236:237], v[234:235], 0, s[100:101]
	v_cvt_pk_bf16_f32 v44, v44, v45
	v_cvt_pk_bf16_f32 v45, v46, v47
	v_cvt_pk_bf16_f32 v46, v40, v41
	v_cvt_pk_bf16_f32 v47, v42, v43
	global_store_dwordx4 v[236:237], v[44:47], off nt
	v_pk_mul_f32 v[36:37], v[36:37], v[228:229] op_sel_hi:[1,0]
	v_pk_mul_f32 v[38:39], v[38:39], v[228:229] op_sel_hi:[1,0]
	v_pk_mul_f32 v[32:33], v[32:33], v[228:229] op_sel_hi:[1,0]
	v_pk_mul_f32 v[34:35], v[34:35], v[228:229] op_sel_hi:[1,0]
	s_mov_b32 s100, 0x401200
	v_lshl_add_u64 v[236:237], v[234:235], 0, s[100:101]
	v_cvt_pk_bf16_f32 v36, v36, v37
	v_cvt_pk_bf16_f32 v37, v38, v39
	v_cvt_pk_bf16_f32 v38, v32, v33
	v_cvt_pk_bf16_f32 v39, v34, v35
	global_store_dwordx4 v[236:237], v[36:39], off nt
	v_pk_mul_f32 v[28:29], v[28:29], v[230:231] op_sel_hi:[1,0]
	v_pk_mul_f32 v[30:31], v[30:31], v[230:231] op_sel_hi:[1,0]
	v_pk_mul_f32 v[24:25], v[24:25], v[230:231] op_sel_hi:[1,0]
	v_pk_mul_f32 v[26:27], v[26:27], v[230:231] op_sel_hi:[1,0]
	s_mov_b32 s100, 0x1400
	v_lshl_add_u64 v[236:237], v[234:235], 0, s[100:101]
	v_cvt_pk_bf16_f32 v28, v28, v29
	v_cvt_pk_bf16_f32 v29, v30, v31
	v_cvt_pk_bf16_f32 v30, v24, v25
	v_cvt_pk_bf16_f32 v31, v26, v27
	global_store_dwordx4 v[236:237], v[28:31], off nt
	v_pk_mul_f32 v[20:21], v[20:21], v[230:231] op_sel_hi:[1,0]
	v_pk_mul_f32 v[22:23], v[22:23], v[230:231] op_sel_hi:[1,0]
	v_pk_mul_f32 v[16:17], v[16:17], v[230:231] op_sel_hi:[1,0]
	v_pk_mul_f32 v[18:19], v[18:19], v[230:231] op_sel_hi:[1,0]
	s_mov_b32 s100, 0x401400
	v_lshl_add_u64 v[236:237], v[234:235], 0, s[100:101]
	v_cvt_pk_bf16_f32 v20, v20, v21
	v_cvt_pk_bf16_f32 v21, v22, v23
	v_cvt_pk_bf16_f32 v22, v16, v17
	v_cvt_pk_bf16_f32 v23, v18, v19
	global_store_dwordx4 v[236:237], v[20:23], off nt
	v_pk_mul_f32 v[12:13], v[12:13], v[232:233] op_sel_hi:[1,0]
	v_pk_mul_f32 v[14:15], v[14:15], v[232:233] op_sel_hi:[1,0]
	v_pk_mul_f32 v[8:9], v[8:9], v[232:233] op_sel_hi:[1,0]
	v_pk_mul_f32 v[10:11], v[10:11], v[232:233] op_sel_hi:[1,0]
	s_mov_b32 s100, 0x1600
	v_lshl_add_u64 v[236:237], v[234:235], 0, s[100:101]
	v_cvt_pk_bf16_f32 v12, v12, v13
	v_cvt_pk_bf16_f32 v13, v14, v15
	v_cvt_pk_bf16_f32 v14, v8, v9
	v_cvt_pk_bf16_f32 v15, v10, v11
	global_store_dwordx4 v[236:237], v[12:15], off nt
	v_pk_mul_f32 v[4:5], v[4:5], v[232:233] op_sel_hi:[1,0]
	v_pk_mul_f32 v[6:7], v[6:7], v[232:233] op_sel_hi:[1,0]
	v_pk_mul_f32 v[0:1], v[0:1], v[232:233] op_sel_hi:[1,0]
	v_pk_mul_f32 v[2:3], v[2:3], v[232:233] op_sel_hi:[1,0]
	s_mov_b32 s100, 0x401600
	v_lshl_add_u64 v[236:237], v[234:235], 0, s[100:101]
	v_cvt_pk_bf16_f32 v4, v4, v5
	v_cvt_pk_bf16_f32 v5, v6, v7
	v_cvt_pk_bf16_f32 v6, v0, v1
	v_cvt_pk_bf16_f32 v7, v2, v3
	global_store_dwordx4 v[236:237], v[4:7], off nt
	s_branch .Lwin_done
; __device__ __forceinline__ unsigned pk2(float lo, float hi) { const f32v2_t v = {lo, hi}; const bf16v2_t b = __builtin_convertvector(v, bf16v2_t); return __builtin_bit_cast(unsigned, b); }
; #define ST_OUT(p, v) __builtin_nontemporal_store((v), (p))
;     __device__ __forceinline__ void operator()(AccRef acc, const Unit& u, int wr, int wc, int fr, int fq) const {
;     ...
;                             if (sg) { const f32v2_t t = av * nrl; f32v2_t e; e.x = __builtin_amdgcn_exp2f(t.x); e.y = __builtin_amdgcn_exp2f(t.y); const f32v2_t d = e + 1.0f;
;                                 hv.x = __builtin_amdgcn_rcpf(d.x); hv.y = __builtin_amdgcn_rcpf(d.y); }
;                             else hv = av * rinv;
;                             ow[n * 2 + jp] = pk2(hv.x, hv.y);
;                         }
;                     u32x4 o; o.x = ow[0]; o.y = ow[1]; o.z = ow[2]; o.w = ow[3];
;                     ST_OUT((u32x4*)(dst + (size_t)row * pitch + bj * bjstep), o);
.Lwin_sg:
	v_mul_f32_e32 v218, 0xbfb8aa3b, v218
	v_mul_f32_e32 v220, 0xbfb8aa3b, v220
	v_mul_f32_e32 v222, 0xbfb8aa3b, v222
	v_mul_f32_e32 v224, 0xbfb8aa3b, v224
	v_mul_f32_e32 v226, 0xbfb8aa3b, v226
	v_mul_f32_e32 v228, 0xbfb8aa3b, v228
	v_mul_f32_e32 v230, 0xbfb8aa3b, v230
	v_mul_f32_e32 v232, 0xbfb8aa3b, v232
	v_pk_mul_f32 v[124:125], v[124:125], v[218:219] op_sel_hi:[1,0]
	v_pk_mul_f32 v[126:127], v[126:127], v[218:219] op_sel_hi:[1,0]
	v_pk_mul_f32 v[120:121], v[120:121], v[218:219] op_sel_hi:[1,0]
	v_pk_mul_f32 v[122:123], v[122:123], v[218:219] op_sel_hi:[1,0]
	v_exp_f32_e32 v124, v124
	v_exp_f32_e32 v125, v125
	v_exp_f32_e32 v126, v126
	v_exp_f32_e32 v127, v127
	v_exp_f32_e32 v120, v120
	v_exp_f32_e32 v121, v121
	v_exp_f32_e32 v122, v122
	v_exp_f32_e32 v123, v123
	v_pk_add_f32 v[124:125], v[124:125], 1.0 op_sel_hi:[1,0]
	v_pk_add_f32 v[126:127], v[126:127], 1.0 op_sel_hi:[1,0]
	v_pk_add_f32 v[120:121], v[120:121], 1.0 op_sel_hi:[1,0]
	v_pk_add_f32 v[122:123], v[122:123], 1.0 op_sel_hi:[1,0]
	v_rcp_f32_e32 v124, v124
	v_rcp_f32_e32 v125, v125
	v_rcp_f32_e32 v126, v126
	v_rcp_f32_e32 v127, v127
	v_rcp_f32_e32 v120, v120
	v_rcp_f32_e32 v121, v121
	v_rcp_f32_e32 v122, v122
	v_rcp_f32_e32 v123, v123
	s_mov_b32 s100, 0x0
	v_lshl_add_u64 v[236:237], v[234:235], 0, s[100:101]
	v_cvt_pk_bf16_f32 v124, v124, v125
	v_cvt_pk_bf16_f32 v125, v126, v127
	v_cvt_pk_bf16_f32 v126, v120, v121
	v_cvt_pk_bf16_f32 v127, v122, v123
	global_store_dwordx4 v[236:237], v[124:127], off nt
	v_pk_mul_f32 v[116:117], v[116:117], v[218:219] op_sel_hi:[1,0]
	v_pk_mul_f32 v[118:119], v[118:119], v[218:219] op_sel_hi:[1,0]
	v_pk_mul_f32 v[112:113], v[112:113], v[218:219] op_sel_hi:[1,0]
	v_pk_mul_f32 v[114:115], v[114:115], v[218:219] op_sel_hi:[1,0]
	v_exp_f32_e32 v116, v116
	v_exp_f32_e32 v117, v117
	v_exp_f32_e32 v118, v118
	v_exp_f32_e32 v119, v119
	v_exp_f32_e32 v112, v112
	v_exp_f32_e32 v113, v113
	v_exp_f32_e32 v114, v114
	v_exp_f32_e32 v115, v115
	v_pk_add_f32 v[116:117], v[116:117], 1.0 op_sel_hi:[1,0]
	v_pk_add_f32 v[118:119], v[118:119], 1.0 op_sel_hi:[1,0]
	v_pk_add_f32 v[112:113], v[112:113], 1.0 op_sel_hi:[1,0]
	v_pk_add_f32 v[114:115], v[114:115], 1.0 op_sel_hi:[1,0]
	v_rcp_f32_e32 v116, v116
	v_rcp_f32_e32 v117, v117
	v_rcp_f32_e32 v118, v118
	v_rcp_f32_e32 v119, v119
	v_rcp_f32_e32 v112, v112
	v_rcp_f32_e32 v113, v113
	v_rcp_f32_e32 v114, v114
	v_rcp_f32_e32 v115, v115
	s_mov_b32 s100, 0x0
	v_lshl_add_u64 v[236:237], v[234:235], 0, s[100:101]
	v_cvt_pk_bf16_f32 v116, v116, v117
	v_cvt_pk_bf16_f32 v117, v118, v119
	v_cvt_pk_bf16_f32 v118, v112, v113
	v_cvt_pk_bf16_f32 v119, v114, v115
	global_store_dwordx4 v[236:237], v[116:119], off offset:256 nt
	v_pk_mul_f32 v[108:109], v[108:109], v[220:221] op_sel_hi:[1,0]
	v_pk_mul_f32 v[110:111], v[110:111], v[220:221] op_sel_hi:[1,0]
	v_pk_mul_f32 v[104:105], v[104:105], v[220:221] op_sel_hi:[1,0]
	v_pk_mul_f32 v[106:107], v[106:107], v[220:221] op_sel_hi:[1,0]
	v_exp_f32_e32 v108, v108
	v_exp_f32_e32 v109, v109
	v_exp_f32_e32 v110, v110
	v_exp_f32_e32 v111, v111
	v_exp_f32_e32 v104, v104
	v_exp_f32_e32 v105, v105
	v_exp_f32_e32 v106, v106
	v_exp_f32_e32 v107, v107
	v_pk_add_f32 v[108:109], v[108:109], 1.0 op_sel_hi:[1,0]
	v_pk_add_f32 v[110:111], v[110:111], 1.0 op_sel_hi:[1,0]
	v_pk_add_f32 v[104:105], v[104:105], 1.0 op_sel_hi:[1,0]
	v_pk_add_f32 v[106:107], v[106:107], 1.0 op_sel_hi:[1,0]
	v_rcp_f32_e32 v108, v108
	v_rcp_f32_e32 v109, v109
	v_rcp_f32_e32 v110, v110
	v_rcp_f32_e32 v111, v111
	v_rcp_f32_e32 v104, v104
	v_rcp_f32_e32 v105, v105
	v_rcp_f32_e32 v106, v106
	v_rcp_f32_e32 v107, v107
	s_mov_b32 s100, 0x50000
	v_lshl_add_u64 v[236:237], v[234:235], 0, s[100:101]
	v_cvt_pk_bf16_f32 v108, v108, v109
	v_cvt_pk_bf16_f32 v109, v110, v111
	v_cvt_pk_bf16_f32 v110, v104, v105
	v_cvt_pk_bf16_f32 v111, v106, v107
	global_store_dwordx4 v[236:237], v[108:111], off nt
	v_pk_mul_f32 v[100:101], v[100:101], v[220:221] op_sel_hi:[1,0]
	v_pk_mul_f32 v[102:103], v[102:103], v[220:221] op_sel_hi:[1,0]
	v_pk_mul_f32 v[96:97], v[96:97], v[220:221] op_sel_hi:[1,0]
	v_pk_mul_f32 v[98:99], v[98:99], v[220:221] op_sel_hi:[1,0]
	v_exp_f32_e32 v100, v100
	v_exp_f32_e32 v101, v101
	v_exp_f32_e32 v102, v102
	v_exp_f32_e32 v103, v103
	v_exp_f32_e32 v96, v96
	v_exp_f32_e32 v97, v97
	v_exp_f32_e32 v98, v98
	v_exp_f32_e32 v99, v99
	v_pk_add_f32 v[100:101], v[100:101], 1.0 op_sel_hi:[1,0]
	v_pk_add_f32 v[102:103], v[102:103], 1.0 op_sel_hi:[1,0]
	v_pk_add_f32 v[96:97], v[96:97], 1.0 op_sel_hi:[1,0]
	v_pk_add_f32 v[98:99], v[98:99], 1.0 op_sel_hi:[1,0]
	v_rcp_f32_e32 v100, v100
	v_rcp_f32_e32 v101, v101
	v_rcp_f32_e32 v102, v102
	v_rcp_f32_e32 v103, v103
	v_rcp_f32_e32 v96, v96
	v_rcp_f32_e32 v97, v97
	v_rcp_f32_e32 v98, v98
	v_rcp_f32_e32 v99, v99
	s_mov_b32 s100, 0x50000
	v_lshl_add_u64 v[236:237], v[234:235], 0, s[100:101]
	v_cvt_pk_bf16_f32 v100, v100, v101
	v_cvt_pk_bf16_f32 v101, v102, v103
	v_cvt_pk_bf16_f32 v102, v96, v97
	v_cvt_pk_bf16_f32 v103, v98, v99
	global_store_dwordx4 v[236:237], v[100:103], off offset:256 nt
	v_pk_mul_f32 v[92:93], v[92:93], v[222:223] op_sel_hi:[1,0]
	v_pk_mul_f32 v[94:95], v[94:95], v[222:223] op_sel_hi:[1,0]
	v_pk_mul_f32 v[88:89], v[88:89], v[222:223] op_sel_hi:[1,0]
	v_pk_mul_f32 v[90:91], v[90:91], v[222:223] op_sel_hi:[1,0]
	v_exp_f32_e32 v92, v92
	v_exp_f32_e32 v93, v93
	v_exp_f32_e32 v94, v94
	v_exp_f32_e32 v95, v95
	v_exp_f32_e32 v88, v88
	v_exp_f32_e32 v89, v89
	v_exp_f32_e32 v90, v90
	v_exp_f32_e32 v91, v91
	v_pk_add_f32 v[92:93], v[92:93], 1.0 op_sel_hi:[1,0]
	v_pk_add_f32 v[94:95], v[94:95], 1.0 op_sel_hi:[1,0]
	v_pk_add_f32 v[88:89], v[88:89], 1.0 op_sel_hi:[1,0]
; __device__ __forceinline__ unsigned pk2(float lo, float hi) { const f32v2_t v = {lo, hi}; const bf16v2_t b = __builtin_convertvector(v, bf16v2_t); return __builtin_bit_cast(unsigned, b); }
; #define ST_OUT(p, v) __builtin_nontemporal_store((v), (p))
;     __device__ __forceinline__ void operator()(AccRef acc, const Unit& u, int wr, int wc, int fr, int fq) const {
;     ...
;                             if (sg) { const f32v2_t t = av * nrl; f32v2_t e; e.x = __builtin_amdgcn_exp2f(t.x); e.y = __builtin_amdgcn_exp2f(t.y); const f32v2_t d = e + 1.0f;
;                                 hv.x = __builtin_amdgcn_rcpf(d.x); hv.y = __builtin_amdgcn_rcpf(d.y); }
;                             else hv = av * rinv;
;                             ow[n * 2 + jp] = pk2(hv.x, hv.y);
;                         }
;                     u32x4 o; o.x = ow[0]; o.y = ow[1]; o.z = ow[2]; o.w = ow[3];
;                     ST_OUT((u32x4*)(dst + (size_t)row * pitch + bj * bjstep), o);
	v_pk_add_f32 v[90:91], v[90:91], 1.0 op_sel_hi:[1,0]
	v_rcp_f32_e32 v92, v92
	v_rcp_f32_e32 v93, v93
	v_rcp_f32_e32 v94, v94
	v_rcp_f32_e32 v95, v95
	v_rcp_f32_e32 v88, v88
	v_rcp_f32_e32 v89, v89
	v_rcp_f32_e32 v90, v90
	v_rcp_f32_e32 v91, v91
	s_mov_b32 s100, 0xa0000
	v_lshl_add_u64 v[236:237], v[234:235], 0, s[100:101]
	v_cvt_pk_bf16_f32 v92, v92, v93
	v_cvt_pk_bf16_f32 v93, v94, v95
	v_cvt_pk_bf16_f32 v94, v88, v89
	v_cvt_pk_bf16_f32 v95, v90, v91
	global_store_dwordx4 v[236:237], v[92:95], off nt
	v_pk_mul_f32 v[84:85], v[84:85], v[222:223] op_sel_hi:[1,0]
	v_pk_mul_f32 v[86:87], v[86:87], v[222:223] op_sel_hi:[1,0]
	v_pk_mul_f32 v[80:81], v[80:81], v[222:223] op_sel_hi:[1,0]
	v_pk_mul_f32 v[82:83], v[82:83], v[222:223] op_sel_hi:[1,0]
	v_exp_f32_e32 v84, v84
	v_exp_f32_e32 v85, v85
	v_exp_f32_e32 v86, v86
	v_exp_f32_e32 v87, v87
	v_exp_f32_e32 v80, v80
	v_exp_f32_e32 v81, v81
	v_exp_f32_e32 v82, v82
	v_exp_f32_e32 v83, v83
	v_pk_add_f32 v[84:85], v[84:85], 1.0 op_sel_hi:[1,0]
	v_pk_add_f32 v[86:87], v[86:87], 1.0 op_sel_hi:[1,0]
	v_pk_add_f32 v[80:81], v[80:81], 1.0 op_sel_hi:[1,0]
	v_pk_add_f32 v[82:83], v[82:83], 1.0 op_sel_hi:[1,0]
	v_rcp_f32_e32 v84, v84
	v_rcp_f32_e32 v85, v85
	v_rcp_f32_e32 v86, v86
	v_rcp_f32_e32 v87, v87
	v_rcp_f32_e32 v80, v80
	v_rcp_f32_e32 v81, v81
	v_rcp_f32_e32 v82, v82
	v_rcp_f32_e32 v83, v83
	s_mov_b32 s100, 0xa0000
	v_lshl_add_u64 v[236:237], v[234:235], 0, s[100:101]
	v_cvt_pk_bf16_f32 v84, v84, v85
	v_cvt_pk_bf16_f32 v85, v86, v87
	v_cvt_pk_bf16_f32 v86, v80, v81
	v_cvt_pk_bf16_f32 v87, v82, v83
	global_store_dwordx4 v[236:237], v[84:87], off offset:256 nt
	v_pk_mul_f32 v[76:77], v[76:77], v[224:225] op_sel_hi:[1,0]
	v_pk_mul_f32 v[78:79], v[78:79], v[224:225] op_sel_hi:[1,0]
	v_pk_mul_f32 v[72:73], v[72:73], v[224:225] op_sel_hi:[1,0]
	v_pk_mul_f32 v[74:75], v[74:75], v[224:225] op_sel_hi:[1,0]
	v_exp_f32_e32 v76, v76
	v_exp_f32_e32 v77, v77
	v_exp_f32_e32 v78, v78
	v_exp_f32_e32 v79, v79
	v_exp_f32_e32 v72, v72
	v_exp_f32_e32 v73, v73
	v_exp_f32_e32 v74, v74
	v_exp_f32_e32 v75, v75
	v_pk_add_f32 v[76:77], v[76:77], 1.0 op_sel_hi:[1,0]
	v_pk_add_f32 v[78:79], v[78:79], 1.0 op_sel_hi:[1,0]
	v_pk_add_f32 v[72:73], v[72:73], 1.0 op_sel_hi:[1,0]
	v_pk_add_f32 v[74:75], v[74:75], 1.0 op_sel_hi:[1,0]
	v_rcp_f32_e32 v76, v76
	v_rcp_f32_e32 v77, v77
	v_rcp_f32_e32 v78, v78
	v_rcp_f32_e32 v79, v79
	v_rcp_f32_e32 v72, v72
	v_rcp_f32_e32 v73, v73
	v_rcp_f32_e32 v74, v74
	v_rcp_f32_e32 v75, v75
	s_mov_b32 s100, 0xf0000
	v_lshl_add_u64 v[236:237], v[234:235], 0, s[100:101]
	v_cvt_pk_bf16_f32 v76, v76, v77
	v_cvt_pk_bf16_f32 v77, v78, v79
	v_cvt_pk_bf16_f32 v78, v72, v73
	v_cvt_pk_bf16_f32 v79, v74, v75
	global_store_dwordx4 v[236:237], v[76:79], off nt
	v_pk_mul_f32 v[68:69], v[68:69], v[224:225] op_sel_hi:[1,0]
	v_pk_mul_f32 v[70:71], v[70:71], v[224:225] op_sel_hi:[1,0]
	v_pk_mul_f32 v[64:65], v[64:65], v[224:225] op_sel_hi:[1,0]
	v_pk_mul_f32 v[66:67], v[66:67], v[224:225] op_sel_hi:[1,0]
	v_exp_f32_e32 v68, v68
	v_exp_f32_e32 v69, v69
	v_exp_f32_e32 v70, v70
	v_exp_f32_e32 v71, v71
	v_exp_f32_e32 v64, v64
	v_exp_f32_e32 v65, v65
	v_exp_f32_e32 v66, v66
	v_exp_f32_e32 v67, v67
	v_pk_add_f32 v[68:69], v[68:69], 1.0 op_sel_hi:[1,0]
	v_pk_add_f32 v[70:71], v[70:71], 1.0 op_sel_hi:[1,0]
	v_pk_add_f32 v[64:65], v[64:65], 1.0 op_sel_hi:[1,0]
	v_pk_add_f32 v[66:67], v[66:67], 1.0 op_sel_hi:[1,0]
	v_rcp_f32_e32 v68, v68
	v_rcp_f32_e32 v69, v69
	v_rcp_f32_e32 v70, v70
	v_rcp_f32_e32 v71, v71
	v_rcp_f32_e32 v64, v64
	v_rcp_f32_e32 v65, v65
	v_rcp_f32_e32 v66, v66
	v_rcp_f32_e32 v67, v67
	s_mov_b32 s100, 0xf0000
	v_lshl_add_u64 v[236:237], v[234:235], 0, s[100:101]
	v_cvt_pk_bf16_f32 v68, v68, v69
	v_cvt_pk_bf16_f32 v69, v70, v71
	v_cvt_pk_bf16_f32 v70, v64, v65
	v_cvt_pk_bf16_f32 v71, v66, v67
	global_store_dwordx4 v[236:237], v[68:71], off offset:256 nt
	v_pk_mul_f32 v[60:61], v[60:61], v[226:227] op_sel_hi:[1,0]
	v_pk_mul_f32 v[62:63], v[62:63], v[226:227] op_sel_hi:[1,0]
	v_pk_mul_f32 v[56:57], v[56:57], v[226:227] op_sel_hi:[1,0]
	v_pk_mul_f32 v[58:59], v[58:59], v[226:227] op_sel_hi:[1,0]
	v_exp_f32_e32 v60, v60
	v_exp_f32_e32 v61, v61
	v_exp_f32_e32 v62, v62
	v_exp_f32_e32 v63, v63
	v_exp_f32_e32 v56, v56
	v_exp_f32_e32 v57, v57
	v_exp_f32_e32 v58, v58
	v_exp_f32_e32 v59, v59
	v_pk_add_f32 v[60:61], v[60:61], 1.0 op_sel_hi:[1,0]
	v_pk_add_f32 v[62:63], v[62:63], 1.0 op_sel_hi:[1,0]
	v_pk_add_f32 v[56:57], v[56:57], 1.0 op_sel_hi:[1,0]
	v_pk_add_f32 v[58:59], v[58:59], 1.0 op_sel_hi:[1,0]
	v_rcp_f32_e32 v60, v60
	v_rcp_f32_e32 v61, v61
	v_rcp_f32_e32 v62, v62
	v_rcp_f32_e32 v63, v63
	v_rcp_f32_e32 v56, v56
	v_rcp_f32_e32 v57, v57
	v_rcp_f32_e32 v58, v58
	v_rcp_f32_e32 v59, v59
	s_mov_b32 s100, 0x280000
	v_lshl_add_u64 v[236:237], v[234:235], 0, s[100:101]
	v_cvt_pk_bf16_f32 v60, v60, v61
	v_cvt_pk_bf16_f32 v61, v62, v63
	v_cvt_pk_bf16_f32 v62, v56, v57
	v_cvt_pk_bf16_f32 v63, v58, v59
	global_store_dwordx4 v[236:237], v[60:63], off nt
	v_pk_mul_f32 v[52:53], v[52:53], v[226:227] op_sel_hi:[1,0]
	v_pk_mul_f32 v[54:55], v[54:55], v[226:227] op_sel_hi:[1,0]
	v_pk_mul_f32 v[48:49], v[48:49], v[226:227] op_sel_hi:[1,0]
	v_pk_mul_f32 v[50:51], v[50:51], v[226:227] op_sel_hi:[1,0]
	v_exp_f32_e32 v52, v52
	v_exp_f32_e32 v53, v53
	v_exp_f32_e32 v54, v54
	v_exp_f32_e32 v55, v55
	v_exp_f32_e32 v48, v48
	v_exp_f32_e32 v49, v49
	v_exp_f32_e32 v50, v50
	v_exp_f32_e32 v51, v51
	v_pk_add_f32 v[52:53], v[52:53], 1.0 op_sel_hi:[1,0]
	v_pk_add_f32 v[54:55], v[54:55], 1.0 op_sel_hi:[1,0]
	v_pk_add_f32 v[48:49], v[48:49], 1.0 op_sel_hi:[1,0]
	v_pk_add_f32 v[50:51], v[50:51], 1.0 op_sel_hi:[1,0]
	v_rcp_f32_e32 v52, v52
; __device__ __forceinline__ unsigned pk2(float lo, float hi) { const f32v2_t v = {lo, hi}; const bf16v2_t b = __builtin_convertvector(v, bf16v2_t); return __builtin_bit_cast(unsigned, b); }
; #define ST_OUT(p, v) __builtin_nontemporal_store((v), (p))
;     __device__ __forceinline__ void operator()(AccRef acc, const Unit& u, int wr, int wc, int fr, int fq) const {
;     ...
;                             if (sg) { const f32v2_t t = av * nrl; f32v2_t e; e.x = __builtin_amdgcn_exp2f(t.x); e.y = __builtin_amdgcn_exp2f(t.y); const f32v2_t d = e + 1.0f;
;                                 hv.x = __builtin_amdgcn_rcpf(d.x); hv.y = __builtin_amdgcn_rcpf(d.y); }
;                             else hv = av * rinv;
;                             ow[n * 2 + jp] = pk2(hv.x, hv.y);
;                         }
;                     u32x4 o; o.x = ow[0]; o.y = ow[1]; o.z = ow[2]; o.w = ow[3];
;                     ST_OUT((u32x4*)(dst + (size_t)row * pitch + bj * bjstep), o);
	v_rcp_f32_e32 v53, v53
	v_rcp_f32_e32 v54, v54
	v_rcp_f32_e32 v55, v55
	v_rcp_f32_e32 v48, v48
	v_rcp_f32_e32 v49, v49
	v_rcp_f32_e32 v50, v50
	v_rcp_f32_e32 v51, v51
	s_mov_b32 s100, 0x280000
	v_lshl_add_u64 v[236:237], v[234:235], 0, s[100:101]
	v_cvt_pk_bf16_f32 v52, v52, v53
	v_cvt_pk_bf16_f32 v53, v54, v55
	v_cvt_pk_bf16_f32 v54, v48, v49
	v_cvt_pk_bf16_f32 v55, v50, v51
	global_store_dwordx4 v[236:237], v[52:55], off offset:256 nt
	v_pk_mul_f32 v[44:45], v[44:45], v[228:229] op_sel_hi:[1,0]
	v_pk_mul_f32 v[46:47], v[46:47], v[228:229] op_sel_hi:[1,0]
	v_pk_mul_f32 v[40:41], v[40:41], v[228:229] op_sel_hi:[1,0]
	v_pk_mul_f32 v[42:43], v[42:43], v[228:229] op_sel_hi:[1,0]
	v_exp_f32_e32 v44, v44
	v_exp_f32_e32 v45, v45
	v_exp_f32_e32 v46, v46
	v_exp_f32_e32 v47, v47
	v_exp_f32_e32 v40, v40
	v_exp_f32_e32 v41, v41
	v_exp_f32_e32 v42, v42
	v_exp_f32_e32 v43, v43
	v_pk_add_f32 v[44:45], v[44:45], 1.0 op_sel_hi:[1,0]
	v_pk_add_f32 v[46:47], v[46:47], 1.0 op_sel_hi:[1,0]
	v_pk_add_f32 v[40:41], v[40:41], 1.0 op_sel_hi:[1,0]
	v_pk_add_f32 v[42:43], v[42:43], 1.0 op_sel_hi:[1,0]
	v_rcp_f32_e32 v44, v44
	v_rcp_f32_e32 v45, v45
	v_rcp_f32_e32 v46, v46
	v_rcp_f32_e32 v47, v47
	v_rcp_f32_e32 v40, v40
	v_rcp_f32_e32 v41, v41
	v_rcp_f32_e32 v42, v42
	v_rcp_f32_e32 v43, v43
	s_mov_b32 s100, 0x2d0000
	v_lshl_add_u64 v[236:237], v[234:235], 0, s[100:101]
	v_cvt_pk_bf16_f32 v44, v44, v45
	v_cvt_pk_bf16_f32 v45, v46, v47
	v_cvt_pk_bf16_f32 v46, v40, v41
	v_cvt_pk_bf16_f32 v47, v42, v43
	global_store_dwordx4 v[236:237], v[44:47], off nt
	v_pk_mul_f32 v[36:37], v[36:37], v[228:229] op_sel_hi:[1,0]
	v_pk_mul_f32 v[38:39], v[38:39], v[228:229] op_sel_hi:[1,0]
	v_pk_mul_f32 v[32:33], v[32:33], v[228:229] op_sel_hi:[1,0]
	v_pk_mul_f32 v[34:35], v[34:35], v[228:229] op_sel_hi:[1,0]
	v_exp_f32_e32 v36, v36
	v_exp_f32_e32 v37, v37
	v_exp_f32_e32 v38, v38
	v_exp_f32_e32 v39, v39
	v_exp_f32_e32 v32, v32
	v_exp_f32_e32 v33, v33
	v_exp_f32_e32 v34, v34
	v_exp_f32_e32 v35, v35
	v_pk_add_f32 v[36:37], v[36:37], 1.0 op_sel_hi:[1,0]
	v_pk_add_f32 v[38:39], v[38:39], 1.0 op_sel_hi:[1,0]
	v_pk_add_f32 v[32:33], v[32:33], 1.0 op_sel_hi:[1,0]
	v_pk_add_f32 v[34:35], v[34:35], 1.0 op_sel_hi:[1,0]
	v_rcp_f32_e32 v36, v36
	v_rcp_f32_e32 v37, v37
	v_rcp_f32_e32 v38, v38
	v_rcp_f32_e32 v39, v39
	v_rcp_f32_e32 v32, v32
	v_rcp_f32_e32 v33, v33
	v_rcp_f32_e32 v34, v34
	v_rcp_f32_e32 v35, v35
	s_mov_b32 s100, 0x2d0000
	v_lshl_add_u64 v[236:237], v[234:235], 0, s[100:101]
	v_cvt_pk_bf16_f32 v36, v36, v37
	v_cvt_pk_bf16_f32 v37, v38, v39
	v_cvt_pk_bf16_f32 v38, v32, v33
	v_cvt_pk_bf16_f32 v39, v34, v35
	global_store_dwordx4 v[236:237], v[36:39], off offset:256 nt
	v_pk_mul_f32 v[28:29], v[28:29], v[230:231] op_sel_hi:[1,0]
	v_pk_mul_f32 v[30:31], v[30:31], v[230:231] op_sel_hi:[1,0]
	v_pk_mul_f32 v[24:25], v[24:25], v[230:231] op_sel_hi:[1,0]
	v_pk_mul_f32 v[26:27], v[26:27], v[230:231] op_sel_hi:[1,0]
	v_exp_f32_e32 v28, v28
	v_exp_f32_e32 v29, v29
	v_exp_f32_e32 v30, v30
	v_exp_f32_e32 v31, v31
	v_exp_f32_e32 v24, v24
	v_exp_f32_e32 v25, v25
	v_exp_f32_e32 v26, v26
	v_exp_f32_e32 v27, v27
	v_pk_add_f32 v[28:29], v[28:29], 1.0 op_sel_hi:[1,0]
	v_pk_add_f32 v[30:31], v[30:31], 1.0 op_sel_hi:[1,0]
	v_pk_add_f32 v[24:25], v[24:25], 1.0 op_sel_hi:[1,0]
	v_pk_add_f32 v[26:27], v[26:27], 1.0 op_sel_hi:[1,0]
	v_rcp_f32_e32 v28, v28
	v_rcp_f32_e32 v29, v29
	v_rcp_f32_e32 v30, v30
	v_rcp_f32_e32 v31, v31
	v_rcp_f32_e32 v24, v24
	v_rcp_f32_e32 v25, v25
	v_rcp_f32_e32 v26, v26
	v_rcp_f32_e32 v27, v27
	s_mov_b32 s100, 0x320000
	v_lshl_add_u64 v[236:237], v[234:235], 0, s[100:101]
	v_cvt_pk_bf16_f32 v28, v28, v29
	v_cvt_pk_bf16_f32 v29, v30, v31
	v_cvt_pk_bf16_f32 v30, v24, v25
	v_cvt_pk_bf16_f32 v31, v26, v27
	global_store_dwordx4 v[236:237], v[28:31], off nt
	v_pk_mul_f32 v[20:21], v[20:21], v[230:231] op_sel_hi:[1,0]
	v_pk_mul_f32 v[22:23], v[22:23], v[230:231] op_sel_hi:[1,0]
	v_pk_mul_f32 v[16:17], v[16:17], v[230:231] op_sel_hi:[1,0]
	v_pk_mul_f32 v[18:19], v[18:19], v[230:231] op_sel_hi:[1,0]
	v_exp_f32_e32 v20, v20
	v_exp_f32_e32 v21, v21
	v_exp_f32_e32 v22, v22
	v_exp_f32_e32 v23, v23
	v_exp_f32_e32 v16, v16
	v_exp_f32_e32 v17, v17
	v_exp_f32_e32 v18, v18
	v_exp_f32_e32 v19, v19
	v_pk_add_f32 v[20:21], v[20:21], 1.0 op_sel_hi:[1,0]
	v_pk_add_f32 v[22:23], v[22:23], 1.0 op_sel_hi:[1,0]
	v_pk_add_f32 v[16:17], v[16:17], 1.0 op_sel_hi:[1,0]
	v_pk_add_f32 v[18:19], v[18:19], 1.0 op_sel_hi:[1,0]
	v_rcp_f32_e32 v20, v20
	v_rcp_f32_e32 v21, v21
	v_rcp_f32_e32 v22, v22
	v_rcp_f32_e32 v23, v23
	v_rcp_f32_e32 v16, v16
	v_rcp_f32_e32 v17, v17
	v_rcp_f32_e32 v18, v18
	v_rcp_f32_e32 v19, v19
	s_mov_b32 s100, 0x320000
	v_lshl_add_u64 v[236:237], v[234:235], 0, s[100:101]
	v_cvt_pk_bf16_f32 v20, v20, v21
	v_cvt_pk_bf16_f32 v21, v22, v23
	v_cvt_pk_bf16_f32 v22, v16, v17
	v_cvt_pk_bf16_f32 v23, v18, v19
	global_store_dwordx4 v[236:237], v[20:23], off offset:256 nt
	v_pk_mul_f32 v[12:13], v[12:13], v[232:233] op_sel_hi:[1,0]
	v_pk_mul_f32 v[14:15], v[14:15], v[232:233] op_sel_hi:[1,0]
	v_pk_mul_f32 v[8:9], v[8:9], v[232:233] op_sel_hi:[1,0]
	v_pk_mul_f32 v[10:11], v[10:11], v[232:233] op_sel_hi:[1,0]
	v_exp_f32_e32 v12, v12
	v_exp_f32_e32 v13, v13
	v_exp_f32_e32 v14, v14
	v_exp_f32_e32 v15, v15
	v_exp_f32_e32 v8, v8
	v_exp_f32_e32 v9, v9
	v_exp_f32_e32 v10, v10
	v_exp_f32_e32 v11, v11
	v_pk_add_f32 v[12:13], v[12:13], 1.0 op_sel_hi:[1,0]
	v_pk_add_f32 v[14:15], v[14:15], 1.0 op_sel_hi:[1,0]
	v_pk_add_f32 v[8:9], v[8:9], 1.0 op_sel_hi:[1,0]
	v_pk_add_f32 v[10:11], v[10:11], 1.0 op_sel_hi:[1,0]
	v_rcp_f32_e32 v12, v12
	v_rcp_f32_e32 v13, v13
	v_rcp_f32_e32 v14, v14
	v_rcp_f32_e32 v15, v15
	v_rcp_f32_e32 v8, v8
	v_rcp_f32_e32 v9, v9
	v_rcp_f32_e32 v10, v10
	v_rcp_f32_e32 v11, v11
	s_mov_b32 s100, 0x370000
	v_lshl_add_u64 v[236:237], v[234:235], 0, s[100:101]
	v_cvt_pk_bf16_f32 v12, v12, v13
	v_cvt_pk_bf16_f32 v13, v14, v15
	v_cvt_pk_bf16_f32 v14, v8, v9
	v_cvt_pk_bf16_f32 v15, v10, v11
	global_store_dwordx4 v[236:237], v[12:15], off nt
	v_pk_mul_f32 v[4:5], v[4:5], v[232:233] op_sel_hi:[1,0]
	v_pk_mul_f32 v[6:7], v[6:7], v[232:233] op_sel_hi:[1,0]
	v_pk_mul_f32 v[0:1], v[0:1], v[232:233] op_sel_hi:[1,0]
	v_pk_mul_f32 v[2:3], v[2:3], v[232:233] op_sel_hi:[1,0]
	v_exp_f32_e32 v4, v4
	v_exp_f32_e32 v5, v5
	v_exp_f32_e32 v6, v6
	v_exp_f32_e32 v7, v7
	v_exp_f32_e32 v0, v0
	v_exp_f32_e32 v1, v1
	v_exp_f32_e32 v2, v2
	v_exp_f32_e32 v3, v3
	v_pk_add_f32 v[4:5], v[4:5], 1.0 op_sel_hi:[1,0]
	v_pk_add_f32 v[6:7], v[6:7], 1.0 op_sel_hi:[1,0]
	v_pk_add_f32 v[0:1], v[0:1], 1.0 op_sel_hi:[1,0]
	v_pk_add_f32 v[2:3], v[2:3], 1.0 op_sel_hi:[1,0]
	v_rcp_f32_e32 v4, v4
	v_rcp_f32_e32 v5, v5
	v_rcp_f32_e32 v6, v6
	v_rcp_f32_e32 v7, v7
	v_rcp_f32_e32 v0, v0
	v_rcp_f32_e32 v1, v1
	v_rcp_f32_e32 v2, v2
	v_rcp_f32_e32 v3, v3
	s_mov_b32 s100, 0x370000
	v_lshl_add_u64 v[236:237], v[234:235], 0, s[100:101]
	v_cvt_pk_bf16_f32 v4, v4, v5
	v_cvt_pk_bf16_f32 v5, v6, v7
	v_cvt_pk_bf16_f32 v6, v0, v1
	v_cvt_pk_bf16_f32 v7, v2, v3
	global_store_dwordx4 v[236:237], v[4:7], off offset:256 nt
; #define PG8_BAR __builtin_amdgcn_s_barrier()
; template <class Epi, class Sched>
; __device__ __forceinline__ void gemm_phase(LAS unsigned char* lds, const Gemm g, const Sched& S, const Epi& E) {
;     ...
;         if (!has_next) break;
; #pragma unroll
;         for (int a = 0; a < 2; ++a)
; #pragma unroll
;             for (int b = 0; b < 2; ++b)
; #pragma unroll
;                 for (int m = 0; m < 4; ++m)
; #pragma unroll
;                     for (int n = 0; n < 2; ++n) acc[a][b][m][n] = (f32x4){0.f, 0.f, 0.f, 0.f};
;         cur = nxt; cA = nA; cB = nB; ++ui;
;         if (Sched::SEGMENTED) nt = S.nt(cur);
;     ...
;         if (wr == 1) PG8_BAR;
;     ...
;     }
.Lwin_done:
	s_andn2_b64 vcc, exec, s[38:39]
	s_mov_b64 s[0:1], -1
	s_cbranch_vccnz .LBB0_378
	s_andn2_b64 vcc, exec, s[44:45]
	s_cbranch_vccnz .LBB0_377
	s_barrier
	s_branch .LBB0_377
